# phase 9: per-row p load issued with the row's other loads (was a second exposed round trip per row)
# speedup vs baseline: 1.0159x; 1.0159x over previous
; __global__ void __launch_bounds__(NWAVES * 64, 2) hymba_fwd(Args args) {
;     ...
;         for (int m = gw; m < MROWS; m += NGW) { const v2u* xr = (const v2u*)(X1B + (size_t)m * DM) + lane; const v2u* mr = (const v2u*)(H + (size_t)m * DM) + lane;
;             f32x4 v[4], mx[4]; float s = 0.f;
; #pragma unroll
;             for (int j = 0; j < 4; ++j) { { const v2u wx = __builtin_nontemporal_load(xr + 64 * j); v[j] = (f32x4){bflo(wx.x), bfhi(wx.x), bflo(wx.y), bfhi(wx.y)}; } const v2u w = __builtin_nontemporal_load(mr + 64 * j); mx[j] = (f32x4){bflo(w.x), bfhi(w.x), bflo(w.y), bfhi(w.y)};
;               s += (mx[j].x * mx[j].x + mx[j].y * mx[j].y) + (mx[j].z * mx[j].z + mx[j].w * mx[j].w); }
.LBB0_824:
	v_lshl_add_u64 v[24:25], s[20:21], 0, v[16:17]
	v_lshl_add_u64 v[22:23], s[16:17], 0, v[16:17]
	v_add_co_u32_e32 v26, vcc, 0x1900000, v24
	global_load_dwordx2 v[28:29], v[22:23], off nt
	global_load_dwordx2 v[30:31], v[22:23], off offset:512 nt
	global_load_dwordx2 v[32:33], v[22:23], off offset:1024 nt
	global_load_dwordx2 v[34:35], v[22:23], off offset:1536 nt
	v_add_co_u32_e64 v22, s[0:1], s28, v24
	v_addc_co_u32_e32 v27, vcc, 0, v25, vcc
	s_nop 0
	v_addc_co_u32_e64 v23, s[0:1], 0, v25, s[0:1]
	global_load_dwordx2 v[24:25], v[26:27], off nt
	global_load_dwordx2 v[36:37], v[26:27], off offset:512 nt
	global_load_dwordx2 v[38:39], v[26:27], off offset:1024 nt
	s_nop 0
	global_load_dwordx2 v[26:27], v[26:27], off offset:1536 nt
	v_mov_b32_e32 v56, 0
	s_add_i32 s24, s10, 0xffff8000
	v_mov_b32_e32 v57, 0
	s_cmp_lt_i32 s10, 0x8000
	s_cselect_b32 s1, s11, 0
	s_cselect_b32 s0, s10, s24
	s_cselect_b32 s25, s41, s43
	s_cselect_b32 s24, s40, s42
	s_lshl_b64 s[0:1], s[0:1], 10
	s_add_u32 s24, s24, s0
	s_addc_u32 s25, s25, s1
	s_add_u32 s10, s10, s34
	s_addc_u32 s11, s11, s35
	global_load_dwordx4 v[100:103], v18, s[24:25] nt
	s_waitcnt vmcnt(8)
	v_lshlrev_b32_e32 v40, 16, v28
	v_and_b32_e32 v41, 0xffff0000, v28
	v_lshlrev_b32_e32 v28, 16, v29
	v_and_b32_e32 v29, 0xffff0000, v29
	s_waitcnt vmcnt(7)
	v_lshlrev_b32_e32 v42, 16, v30
	v_and_b32_e32 v43, 0xffff0000, v30
	v_lshlrev_b32_e32 v30, 16, v31
	s_waitcnt vmcnt(4)
	v_lshlrev_b32_e32 v48, 16, v24
	v_and_b32_e32 v49, 0xffff0000, v24
	v_lshlrev_b32_e32 v24, 16, v25
	v_and_b32_e32 v25, 0xffff0000, v25
	s_waitcnt vmcnt(3)
	v_lshlrev_b32_e32 v50, 16, v36
	v_and_b32_e32 v51, 0xffff0000, v36
	v_lshlrev_b32_e32 v36, 16, v37
	v_and_b32_e32 v37, 0xffff0000, v37
	s_waitcnt vmcnt(2)
	v_lshlrev_b32_e32 v52, 16, v38
	v_and_b32_e32 v53, 0xffff0000, v38
	v_lshlrev_b32_e32 v38, 16, v39
	v_and_b32_e32 v39, 0xffff0000, v39
	v_mul_f32_e32 v58, v49, v49
	v_mul_f32_e32 v59, v25, v25
	v_mul_f32_e32 v60, v51, v51
	v_mul_f32_e32 v61, v37, v37
	s_waitcnt vmcnt(1)
; __device__ __forceinline__ unsigned pk2(float lo, float hi) { return f2bf(lo) | (f2bf(hi) << 16); }
; __global__ void __launch_bounds__(NWAVES * 64, 2) hymba_fwd(Args args) {
;     ...
;               s += (mx[j].x * mx[j].x + mx[j].y * mx[j].y) + (mx[j].z * mx[j].z + mx[j].w * mx[j].w); }
;             const float rs = 1.0f / sqrtf(wave_sum(s) * (1.0f / DM) + EPS);
;             v2u* o8 = (v2u*)(X2B + (size_t)m * DM) + lane;
; #pragma unroll
;             for (int j = 0; j < 4; ++j) { v[j] = v[j] + mx[j] * rs * g1[j]; v2u w; w.x = pk2(v[j].x, v[j].y); w.y = pk2(v[j].z, v[j].w); o8[64 * j] = w; }
;             const f32x4 pv = __builtin_nontemporal_load((const f32x4*)prow_ptr(args, m) + lane); v2u w; w.x = pk2(pv.x, pv.y); w.y = pk2(pv.z, pv.w); *((v2u*)(PB + (size_t)m * 256) + lane) = w; }
	v_lshlrev_b32_e32 v54, 16, v26
	v_and_b32_e32 v55, 0xffff0000, v26
	v_lshlrev_b32_e32 v26, 16, v27
	v_and_b32_e32 v27, 0xffff0000, v27
	v_mul_f32_e32 v62, v53, v53
	v_mul_f32_e32 v63, v39, v39
	v_fmac_f32_e32 v58, v48, v48
	v_fmac_f32_e32 v59, v24, v24
	v_fmac_f32_e32 v60, v50, v50
	v_fmac_f32_e32 v61, v36, v36
	v_mul_f32_e32 v64, v55, v55
	v_mul_f32_e32 v65, v27, v27
	v_fmac_f32_e32 v62, v52, v52
	v_fmac_f32_e32 v63, v38, v38
	v_add_f32_e32 v58, v58, v59
	v_add_f32_e32 v59, v60, v61
	v_fmac_f32_e32 v64, v54, v54
	v_fmac_f32_e32 v65, v26, v26
	v_add_f32_e32 v60, v62, v63
	v_add_f32_e32 v58, v58, v59
	v_add_f32_e32 v61, v64, v65
	v_add_f32_e32 v58, v58, v60
	v_add_f32_e32 v58, v58, v61
	v_and_b32_e32 v31, 0xffff0000, v31
	v_lshlrev_b32_e32 v44, 16, v32
	v_add_f32_dpp v58, v58, v58 quad_perm:[1,0,3,2] row_mask:0xf bank_mask:0xf bound_ctrl:1
	v_and_b32_e32 v45, 0xffff0000, v32
	v_lshlrev_b32_e32 v32, 16, v33
	v_add_f32_dpp v58, v58, v58 quad_perm:[2,3,0,1] row_mask:0xf bank_mask:0xf bound_ctrl:1
	v_and_b32_e32 v33, 0xffff0000, v33
	v_lshlrev_b32_e32 v46, 16, v34
	v_add_f32_dpp v58, v58, v58 row_half_mirror row_mask:0xf bank_mask:0xf bound_ctrl:1
	v_and_b32_e32 v47, 0xffff0000, v34
	v_lshlrev_b32_e32 v34, 16, v35
	v_add_f32_dpp v58, v58, v58 row_mirror row_mask:0xf bank_mask:0xf bound_ctrl:1
	v_and_b32_e32 v35, 0xffff0000, v35
	s_nop 0
	v_mov_b32_dpp v56, v58 row_bcast:15 row_mask:0xa bank_mask:0xf
	v_add_f32_e32 v56, v58, v56
	s_nop 1
	v_mov_b32_dpp v57, v56 row_bcast:31 row_mask:0xc bank_mask:0xf
	v_add_f32_e32 v56, v56, v57
	s_nop 0
	v_readlane_b32 s0, v56, 63
	s_nop 1
	v_fma_f32 v56, s0, v20, v19
	v_mul_f32_e32 v57, 0x4f800000, v56
	v_cmp_gt_f32_e32 vcc, s26, v56
	s_nop 1
	v_cndmask_b32_e32 v56, v56, v57, vcc
	v_sqrt_f32_e32 v57, v56
	s_nop 0
	v_add_u32_e32 v58, -1, v57
	v_add_u32_e32 v59, 1, v57
	v_fma_f32 v60, -v58, v57, v56
	v_fma_f32 v61, -v59, v57, v56
	v_cmp_ge_f32_e64 s[0:1], 0, v60
	s_nop 1
	v_cndmask_b32_e64 v57, v57, v58, s[0:1]
	v_cmp_lt_f32_e64 s[0:1], 0, v61
	s_nop 1
	v_cndmask_b32_e64 v57, v57, v59, s[0:1]
	v_mul_f32_e32 v58, 0x37800000, v57
	v_cndmask_b32_e32 v57, v57, v58, vcc
	v_cmp_class_f32_e32 vcc, v56, v21
	s_nop 1
	v_cndmask_b32_e32 v56, v57, v56, vcc
	v_div_scale_f32 v57, s[0:1], v56, v56, 1.0
	v_rcp_f32_e32 v59, v57
	v_div_scale_f32 v58, vcc, 1.0, v56, 1.0
	v_fma_f32 v60, -v57, v59, 1.0
	v_fmac_f32_e32 v59, v60, v59
	v_mul_f32_e32 v60, v58, v59
	v_fma_f32 v61, -v57, v60, v58
	v_fmac_f32_e32 v60, v61, v59
	v_fma_f32 v57, -v57, v60, v58
	v_div_fmas_f32 v57, v57, v59, v60
	v_div_fixup_f32 v56, v57, v56, 1.0
	v_pk_mul_f32 v[48:49], v[56:57], v[48:49] op_sel_hi:[0,1]
	v_pk_mul_f32 v[24:25], v[56:57], v[24:25] op_sel_hi:[0,1]
	v_pk_mul_f32 v[50:51], v[56:57], v[50:51] op_sel_hi:[0,1]
	v_pk_mul_f32 v[36:37], v[56:57], v[36:37] op_sel_hi:[0,1]
	v_pk_mul_f32 v[52:53], v[56:57], v[52:53] op_sel_hi:[0,1]
	v_pk_mul_f32 v[38:39], v[56:57], v[38:39] op_sel_hi:[0,1]
	v_pk_mul_f32 v[54:55], v[56:57], v[54:55] op_sel_hi:[0,1]
	v_pk_mul_f32 v[26:27], v[56:57], v[26:27] op_sel_hi:[0,1]
	v_pk_fma_f32 v[24:25], v[24:25], v[2:3], v[28:29]
	v_pk_fma_f32 v[28:29], v[48:49], v[0:1], v[40:41]
	v_pk_fma_f32 v[30:31], v[36:37], v[6:7], v[30:31]
	v_pk_fma_f32 v[36:37], v[50:51], v[4:5], v[42:43]
	v_pk_fma_f32 v[32:33], v[38:39], v[10:11], v[32:33]
	v_pk_fma_f32 v[38:39], v[52:53], v[8:9], v[44:45]
	v_pk_fma_f32 v[26:27], v[26:27], v[14:15], v[34:35]
	v_pk_fma_f32 v[34:35], v[54:55], v[12:13], v[46:47]
	v_bfe_u32 v40, v28, 16, 1
	v_bfe_u32 v42, v24, 16, 1
	v_bfe_u32 v41, v29, 16, 1
	v_bfe_u32 v43, v25, 16, 1
	v_bfe_u32 v44, v36, 16, 1
	v_bfe_u32 v46, v30, 16, 1
	v_bfe_u32 v48, v38, 16, 1
	v_bfe_u32 v50, v32, 16, 1
	v_bfe_u32 v52, v34, 16, 1
	v_bfe_u32 v54, v26, 16, 1
	v_bfe_u32 v55, v27, 16, 1
	v_add3_u32 v28, v28, v40, s27
	v_add3_u32 v24, v24, v42, s27
	v_bfe_u32 v45, v37, 16, 1
	v_bfe_u32 v47, v31, 16, 1
	v_bfe_u32 v49, v39, 16, 1
	v_bfe_u32 v51, v33, 16, 1
	v_bfe_u32 v53, v35, 16, 1
	v_add3_u32 v29, v29, v41, s27
	v_add3_u32 v25, v25, v43, s27
	v_add3_u32 v36, v36, v44, s27
	v_add3_u32 v30, v30, v46, s27
	v_add3_u32 v38, v38, v48, s27
	v_add3_u32 v32, v32, v50, s27
	v_add3_u32 v34, v34, v52, s27
	v_add3_u32 v26, v26, v54, s27
	v_add3_u32 v40, v27, v55, s27
	v_lshrrev_b32_e32 v27, 16, v28
	v_lshrrev_b32_e32 v28, 16, v24
	v_add3_u32 v37, v37, v45, s27
	v_add3_u32 v31, v31, v47, s27
	v_add3_u32 v39, v39, v49, s27
	v_add3_u32 v33, v33, v51, s27
	v_add3_u32 v35, v35, v53, s27
	v_lshrrev_b32_e32 v36, 16, v36
	v_lshrrev_b32_e32 v30, 16, v30
	v_lshrrev_b32_e32 v38, 16, v38
	v_lshrrev_b32_e32 v32, 16, v32
	v_lshrrev_b32_e32 v34, 16, v34
	v_lshrrev_b32_e32 v41, 16, v26
	v_and_or_b32 v24, v29, s3, v27
	v_and_or_b32 v25, v25, s3, v28
	v_and_or_b32 v26, v37, s3, v36
	v_and_or_b32 v27, v31, s3, v30
	v_and_or_b32 v28, v39, s3, v38
	v_and_or_b32 v29, v33, s3, v32
	v_and_or_b32 v30, v35, s3, v34
	v_and_or_b32 v31, v40, s3, v41
	global_store_dwordx2 v[22:23], v[24:25], off
	global_store_dwordx2 v[22:23], v[26:27], off offset:512
	global_store_dwordx2 v[22:23], v[28:29], off offset:1024
	global_store_dwordx2 v[22:23], v[30:31], off offset:1536
	v_lshl_add_u64 v[26:27], s[12:13], 0, v[16:17]
	s_add_u32 s12, s12, s14
	s_addc_u32 s13, s13, s15
	s_add_u32 s16, s16, s18
	s_addc_u32 s17, s17, s19
	s_add_u32 s20, s20, s18
	s_addc_u32 s21, s21, s19
	s_cmp_gt_i32 s10, 0xbfff
	s_waitcnt vmcnt(4)
	v_bfe_u32 v28, v100, 16, 1
	v_bfe_u32 v30, v102, 16, 1
	v_bfe_u32 v29, v101, 16, 1
	v_bfe_u32 v31, v103, 16, 1
	v_add3_u32 v22, v100, v28, s27
	v_add3_u32 v24, v102, v30, s27
	v_add3_u32 v23, v101, v29, s27
	v_add3_u32 v25, v103, v31, s27
	v_lshrrev_b32_e32 v22, 16, v22
	v_lshrrev_b32_e32 v24, 16, v24
	v_and_or_b32 v22, v23, s3, v22
	v_and_or_b32 v23, v25, s3, v24
	global_store_dwordx2 v[26:27], v[22:23], off
	s_cbranch_scc0 .LBB0_824
